# P4 retention output stage: hoist 7 serialized gain loads + 4 gate loads out of the store/load/wait chain
# speedup vs baseline: 1.0021x; 1.0021x over previous
.LBB0_548:
	s_or_b32 s58, s88, s87
	v_add_lshl_u32 v96, s58, v168, 6
	s_add_i32 s58, s58, s74
	v_lshl_add_u64 v[0:1], v[98:99], 0, v[96:97]
	s_lshl_b32 s75, s58, 6
	v_mad_u64_u32 v[12:13], s[58:59], v0, s35, v[158:159]
	s_add_u32 s59, s82, s75
	v_mov_b64_e32 v[16:17], s[20:21]
	v_or_b32_e32 v18, s59, v176
	s_addc_u32 s58, s83, 0
	v_or_b32_e32 v68, s59, v118
	s_add_i32 s59, s88, s74
	v_mad_u64_u32 v[16:17], s[88:89], v18, s35, v[16:17]
	v_mad_i32_i24 v17, s58, v196, v17
	v_mov_b32_e32 v117, v97
	v_mad_u64_u32 v[20:21], s[88:89], v68, s35, v[120:121]
	v_lshl_add_u64 v[22:23], v[16:17], 0, s[4:5]
	v_mad_i32_i24 v13, v1, s35, v13
	v_mad_i32_i24 v21, s58, v196, v21
	v_lshl_add_u64 v[24:25], v[22:23], 0, v[116:117]
	global_load_dwordx4 v[0:3], v[12:13], off offset:2096
	global_load_dwordx4 v[4:7], v[12:13], off offset:2080
	global_load_dwordx4 v[8:11], v[12:13], off offset:2064
	s_nop 0
	global_load_dwordx4 v[12:15], v[12:13], off offset:2048
	s_nop 0
	global_load_dwordx4 v[16:19], v[20:21], off
	global_load_dwordx4 v[70:73], v[20:21], off offset:32
	global_load_dwordx4 v[74:77], v[20:21], off offset:64
	global_load_dwordx4 v[64:67], v[20:21], off offset:96
	v_add_co_u32_e32 v26, vcc, s73, v24
	global_load_dwordx4 v[20:23], v[24:25], off offset:1024
	s_nop 0
	v_addc_co_u32_e32 v27, vcc, 0, v25, vcc
	v_lshl_add_u64 v[28:29], v[24:25], 0, s[78:79]
	global_load_dwordx4 v[78:81], v[24:25], off offset:1056
	global_load_dwordx4 v[82:85], v[24:25], off offset:1088
	global_load_dwordx4 v[86:89], v[24:25], off offset:1120
	s_nop 0
	global_load_dwordx4 v[24:27], v[26:27], off offset:1024
	s_nop 0
	global_load_dwordx4 v[90:93], v[28:29], off offset:32
	global_load_dwordx4 v[164:167], v[28:29], off offset:64
	global_load_dwordx4 v[198:201], v[28:29], off offset:96
	s_mulk_i32 s59, 0x2400
	v_add_u32_e32 v69, s59, v181
	s_waitcnt vmcnt(12)
	ds_write_b128 v191, v[12:15]
	ds_write_b128 v191, v[8:11] offset:16
	ds_write_b128 v191, v[4:7] offset:32
	ds_write_b128 v191, v[0:3] offset:48
	s_waitcnt vmcnt(7)
	v_mfma_f32_32x32x16_bf16 v[48:63], v[20:23], v[16:19], 0
	s_waitcnt lgkmcnt(0)
	s_barrier
	ds_read_b128 v[0:3], v69 offset:36864
	ds_read_b128 v[202:205], v69 offset:36896
	ds_read_b128 v[20:23], v69 offset:41472
	ds_read_b128 v[206:209], v69 offset:41504
	s_waitcnt lgkmcnt(3)
	v_mfma_f32_32x32x16_bf16 v[0:15], v[0:3], v[16:19], 0
	s_waitcnt vmcnt(3)
	v_mfma_f32_32x32x16_bf16 v[32:47], v[24:27], v[16:19], 0
	v_mfma_f32_32x32x16_bf16 v[48:63], v[78:81], v[70:73], v[48:63]
	s_waitcnt lgkmcnt(1)
	v_mfma_f32_32x32x16_bf16 v[16:31], v[20:23], v[16:19], 0
	v_mfma_f32_32x32x16_bf16 v[0:15], v[202:205], v[70:73], v[0:15]
	s_waitcnt vmcnt(2)
	v_mfma_f32_32x32x16_bf16 v[32:47], v[90:93], v[70:73], v[32:47]
	v_mfma_f32_32x32x16_bf16 v[48:63], v[82:85], v[74:77], v[48:63]
	s_waitcnt lgkmcnt(0)
	v_mfma_f32_32x32x16_bf16 v[16:31], v[206:209], v[70:73], v[16:31]
	ds_read_b128 v[70:73], v69 offset:36928
	ds_read_b128 v[78:81], v69 offset:36960
	s_waitcnt lgkmcnt(1)
	v_mfma_f32_32x32x16_bf16 v[0:15], v[70:73], v[74:77], v[0:15]
	ds_read_b128 v[70:73], v69 offset:41536
	ds_read_b128 v[82:85], v69 offset:41568
	v_mov_b32_e32 v69, s58
	s_waitcnt vmcnt(1)
	v_mfma_f32_32x32x16_bf16 v[32:47], v[164:167], v[74:77], v[32:47]
	v_mad_u64_u32 v[166:167], s[88:89], v68, s35, v[160:161]
	v_lshlrev_b64 v[68:69], 11, v[68:69]
	v_lshl_add_u64 v[164:165], v[162:163], 0, v[68:69]
	ds_read_b64_tr_b16 v[68:69], v197
	v_mad_i32_i24 v167, s58, v196, v167
	s_mov_b32 s88, 4
	v_mfma_f32_32x32x16_bf16 v[48:63], v[86:89], v[64:67], v[48:63]
	s_waitcnt lgkmcnt(2)
	v_mfma_f32_32x32x16_bf16 v[16:31], v[70:73], v[74:77], v[16:31]
	s_nop 9
	v_mul_f32_e64 v48, v124, v48
	v_mul_f32_e64 v49, v125, v49
	v_mul_f32_e64 v50, v128, v50
	v_mul_f32_e64 v51, v129, v51
	v_mul_f32_e64 v52, v132, v52
	v_mul_f32_e64 v53, v133, v53
	v_pk_mul_f32 v[54:55], v[136:137], v[54:55]
	v_cvt_pk_bf16_f32 v48, v48, v49
	v_cvt_pk_bf16_f32 v49, v50, v51
	v_cvt_pk_bf16_f32 v50, v52, v53
	v_cvt_pk_bf16_f32 v51, v54, v55
	s_waitcnt vmcnt(0)
	v_mfma_f32_32x32x16_bf16 v[32:47], v[198:201], v[64:67], v[32:47]
	ds_read_b64_tr_b16 v[70:71], v197 offset:1152
	ds_read_b64_tr_b16 v[74:75], v197 offset:1216
	ds_read_b64_tr_b16 v[72:73], v197 offset:64
	ds_read_b64_tr_b16 v[198:199], v197 offset:2304
	ds_read_b64_tr_b16 v[200:201], v197 offset:3456
	ds_read_b64_tr_b16 v[204:205], v197 offset:3520
	ds_read_b64_tr_b16 v[202:203], v197 offset:2368
	v_pk_mul_f32 v[52:53], v[140:141], v[56:57]
	v_pk_mul_f32 v[54:55], v[152:153], v[62:63]
	ds_read_b64_tr_b16 v[206:207], v197 offset:4608
	ds_read_b64_tr_b16 v[208:209], v197 offset:5760
	ds_read_b64_tr_b16 v[212:213], v197 offset:5824
	ds_read_b64_tr_b16 v[210:211], v197 offset:4672
	ds_read_b64_tr_b16 v[214:215], v197 offset:6912
	ds_read_b64_tr_b16 v[216:217], v197 offset:8064
	v_pk_mul_f32 v[32:33], v[126:127], v[32:33]
	v_mfma_f32_32x32x16_bf16 v[0:15], v[78:81], v[64:67], v[0:15]
	v_mul_f32_e64 v36, v134, v36
	v_mul_f32_e64 v37, v135, v37
	v_mul_f32_e64 v38, v138, v38
	v_mul_f32_e64 v39, v139, v39
	v_cvt_pk_bf16_f32 v36, v36, v37
	v_cvt_pk_bf16_f32 v37, v38, v39
	v_pk_mul_f32 v[38:39], v[142:143], v[40:41]
	v_pk_mul_f32 v[40:41], v[146:147], v[42:43]
	v_pk_mul_f32 v[42:43], v[150:151], v[44:45]
	s_waitcnt lgkmcnt(14)
	v_mfma_f32_32x32x16_bf16 v[16:31], v[82:85], v[64:67], v[16:31]
	v_mul_f32_e64 v44, v154, v46
	v_mul_f32_e64 v45, v155, v47
	v_mov_b32_e32 v46, v4
	v_mul_f32_e32 v4, v122, v6
	v_mul_f32_e32 v12, v122, v12
	s_waitcnt lgkmcnt(12)
	v_mfma_f32_32x32x16_bf16 v[80:95], v[68:71], v[48:51], 0
	s_nop 4
	v_mul_f32_e32 v6, v122, v22
	v_mov_b32_e32 v22, v7
	v_mov_b32_e32 v47, v20
	v_mul_f32_e32 v20, v122, v9
	s_waitcnt lgkmcnt(10)
	v_mfma_f32_32x32x16_bf16 v[64:79], v[72:75], v[48:51], 0
	v_mul_f32_e64 v48, v144, v58
	v_mul_f32_e64 v49, v145, v59
	v_mul_f32_e64 v50, v148, v60
	v_mul_f32_e64 v51, v149, v61
	v_cvt_pk_bf16_f32 v58, v52, v53
	v_cvt_pk_bf16_f32 v59, v48, v49
	v_cvt_pk_bf16_f32 v60, v50, v51
	v_cvt_pk_bf16_f32 v61, v54, v55
	s_waitcnt lgkmcnt(8)
	s_nop 0
	v_mfma_f32_32x32x16_bf16 v[80:95], v[198:201], v[58:61], v[80:95]
	ds_read_b64_tr_b16 v[200:201], v197 offset:8128
	ds_read_b64_tr_b16 v[198:199], v197 offset:6976
	global_load_dwordx4 v[48:51], v[156:157], off
	global_load_dwordx2 v[56:57], v[166:167], off offset:3072
	global_load_dwordx2 v[54:55], v[166:167], off offset:3088
	global_load_dwordx2 v[52:53], v[166:167], off offset:3104
	s_waitcnt lgkmcnt(8)
	v_mfma_f32_32x32x16_bf16 v[64:79], v[202:205], v[58:61], v[64:79]
	v_mul_f32_e64 v58, v130, v34
	v_mul_f32_e64 v59, v131, v35
	v_cvt_pk_bf16_f32 v34, v32, v33
	v_cvt_pk_bf16_f32 v35, v58, v59
	global_load_dwordx2 v[32:33], v[166:167], off offset:3120
	global_load_dwordx4 v[224:227], v[156:157], off offset:32
	global_load_dwordx4 v[228:231], v[156:157], off offset:64
	global_load_dwordx4 v[232:235], v[156:157], off offset:96
	global_load_dwordx4 v[236:239], v[156:157], off offset:128
	global_load_dwordx4 v[240:243], v[156:157], off offset:160
	global_load_dwordx4 v[244:247], v[156:157], off offset:192
	global_load_dwordx4 v[248:251], v[156:157], off offset:224
	s_waitcnt lgkmcnt(6)
	v_mfma_f32_32x32x16_bf16 v[80:95], v[206:209], v[34:37], v[80:95]
	s_waitcnt lgkmcnt(4)
	v_mfma_f32_32x32x16_bf16 v[64:79], v[210:213], v[34:37], v[64:79]
	v_cvt_pk_bf16_f32 v34, v38, v39
	v_cvt_pk_bf16_f32 v35, v40, v41
	v_cvt_pk_bf16_f32 v36, v42, v43
	v_cvt_pk_bf16_f32 v37, v44, v45
	v_mul_f32_e32 v38, v122, v25
	v_mul_f32_e32 v40, v122, v28
	v_mov_b32_e32 v28, v13
	s_waitcnt lgkmcnt(2)
	v_mfma_f32_32x32x16_bf16 v[80:95], v[214:217], v[34:37], v[80:95]
	v_mul_f32_e32 v42, v122, v15
	v_mul_f32_e32 v44, v122, v31
	s_waitcnt lgkmcnt(0)
	v_mfma_f32_32x32x16_bf16 v[64:79], v[198:201], v[34:37], v[64:79]
	global_load_dwordx2 v[206:207], v[166:167], off offset:3136
	global_load_dwordx2 v[208:209], v[166:167], off offset:3152
	global_load_dwordx2 v[210:211], v[166:167], off offset:3168
	global_load_dwordx2 v[212:213], v[166:167], off offset:3184
	s_nop 7
	v_mov_b32_e32 v36, v87
	v_fma_f32 v0, v122, v0, v80
	v_fma_f32 v1, v123, v1, v81
	v_mov_b32_e32 v34, v84
	v_fma_f32 v9, v122, v5, v85
	v_pk_fma_f32 v[2:3], v[122:123], v[2:3], v[82:83]
	v_mov_b32_e32 v87, v9
	v_fma_f32 v15, v122, v8, v88
	v_mov_b32_e32 v37, v71
	v_pk_fma_f32 v[16:17], v[122:123], v[16:17], v[64:65]
	v_pk_fma_f32 v[22:23], v[122:123], v[22:23], v[36:37]
	v_pk_add_f32 v[36:37], v[0:1], v[16:17]
	v_mov_b32_e32 v35, v68
	v_fma_f32 v5, v122, v21, v69
	v_fma_f32 v21, v122, v24, v72
	v_mov_b32_e32 v24, v93
	v_mov_b32_e32 v25, v77
	v_pk_fma_f32 v[18:19], v[122:123], v[18:19], v[66:67]
	v_add_f32_e32 v7, 0, v36
	v_pk_fma_f32 v[34:35], v[122:123], v[46:47], v[34:35]
	v_pk_fma_f32 v[24:25], v[122:123], v[28:29], v[24:25]
	v_pk_add_f32 v[28:29], v[2:3], v[18:19]
	v_add_f32_e32 v7, v37, v7
	v_pk_add_f32 v[62:63], v[34:35], v[34:35] op_sel_hi:[0,1]
	v_add_f32_e32 v7, v28, v7
	v_mov_b32_e32 v71, v63
	v_add_f32_e32 v7, v29, v7
	v_pk_add_f32 v[68:69], v[86:87], v[4:5]
	v_mov_b32_e32 v8, v34
	v_mov_b32_e32 v4, v35
	v_fma_f32 v31, v122, v14, v94
	v_mov_b32_e32 v14, v89
	v_fma_f32 v43, v122, v30, v78
	v_mov_b32_e32 v30, v95
	v_pk_add_f32 v[46:47], v[14:15], v[20:21]
	v_mov_b32_e32 v20, v21
	v_pk_add_f32 v[64:65], v[22:23], v[22:23] op_sel_hi:[0,1]
	v_pk_add_f32 v[58:59], v[30:31], v[42:43]
	v_mov_b32_e32 v64, v73
	v_pk_fma_f32 v[10:11], v[122:123], v[10:11], v[90:91]
	s_waitcnt vmcnt(14)
	v_lshlrev_b32_e32 v28, 16, v57
	v_and_b32_e32 v29, 0xffff0000, v57
	v_lshlrev_b32_e32 v34, 16, v56
	v_and_b32_e32 v35, 0xffff0000, v56
	v_pk_add_f32 v[56:57], v[70:71], v[6:7]
	v_mul_f32_e32 v21, 0xbfb8aa3b, v34
	v_pk_add_f32 v[6:7], v[68:69], v[56:57]
	v_mul_f32_e32 v39, 0xbfb8aa3b, v28
	v_mul_f32_e32 v41, 0xbfb8aa3b, v29
	v_pk_add_f32 v[6:7], v[6:7], v[6:7] op_sel_hi:[0,1]
	v_exp_f32_e32 v42, v21
	v_exp_f32_e32 v45, v39
	v_exp_f32_e32 v41, v41
	v_mov_b32_e32 v39, v7
	v_pk_add_f32 v[6:7], v[64:65], v[38:39]
	v_pk_fma_f32 v[26:27], v[122:123], v[26:27], v[74:75]
	v_mov_b32_e32 v69, v22
	v_mov_b32_e32 v57, v23
	v_pk_add_f32 v[22:23], v[46:47], v[6:7]
	v_pk_add_f32 v[60:61], v[10:11], v[26:27]
	v_mov_b32_e32 v21, v6
	v_pk_add_f32 v[6:7], v[22:23], v[22:23] op_sel_hi:[0,1]
	v_mov_b32_e32 v93, v11
	v_mov_b32_e32 v13, v27
	v_mov_b32_e32 v77, v60
	v_add_f32_e32 v38, 1.0, v42
	v_add_f32_e32 v6, 1.0, v45
	v_add_f32_e32 v39, 1.0, v41
	v_mov_b32_e32 v41, v7
	v_pk_add_f32 v[12:13], v[92:93], v[12:13]
	v_rcp_f32_e32 v22, v38
	v_rcp_f32_e32 v38, v6
	v_pk_add_f32 v[6:7], v[76:77], v[40:41]
	v_mov_b32_e32 v37, v12
	v_pk_add_f32 v[12:13], v[12:13], v[6:7]
	v_pk_add_f32 v[66:67], v[24:25], v[24:25] op_sel_hi:[0,1]
	v_mov_b32_e32 v36, v24
	v_pk_mov_b32 v[24:25], v[24:25], v[6:7] op_sel:[1,0]
	v_pk_add_f32 v[6:7], v[12:13], v[12:13] op_sel_hi:[0,1]
	v_mov_b32_e32 v66, v79
	v_mov_b32_e32 v45, v7
	v_pk_add_f32 v[12:13], v[66:67], v[44:45]
	v_mul_f32_e32 v30, 0xbfb8aa3b, v35
	v_pk_add_f32 v[6:7], v[58:59], v[12:13]
	v_exp_f32_e32 v30, v30
	v_add_f32_e32 v6, v6, v7
	ds_bpermute_b32 v7, v169, v6
	v_mov_b32_e32 v14, v15
	v_add_f32_e32 v30, 1.0, v30
	v_rcp_f32_e32 v23, v30
	v_mov_b32_e32 v15, v46
	s_waitcnt lgkmcnt(0)
	v_add_f32_e32 v6, v6, v7
	v_mul_f32_e32 v30, 0x3c800000, v6
	v_mov_b32_e32 v59, v31
	v_pk_add_f32 v[16:17], v[16:17], v[30:31] op_sel_hi:[1,0] neg_lo:[0,1] neg_hi:[0,1]
	v_mov_b32_e32 v13, v43
	v_pk_add_f32 v[40:41], v[0:1], v[30:31] op_sel_hi:[1,0] neg_lo:[0,1] neg_hi:[0,1]
	v_pk_add_f32 v[44:45], v[10:11], v[30:31] op_sel_hi:[1,0] neg_lo:[0,1] neg_hi:[0,1]
	v_pk_add_f32 v[0:1], v[24:25], v[30:31] op_sel_hi:[1,0] neg_lo:[0,1] neg_hi:[0,1]
	v_pk_add_f32 v[24:25], v[58:59], v[30:31] op_sel_hi:[1,0] neg_lo:[0,1] neg_hi:[0,1]
	v_pk_add_f32 v[58:59], v[14:15], v[30:31] op_sel_hi:[1,0] neg_lo:[0,1] neg_hi:[0,1]
	v_pk_add_f32 v[14:15], v[18:19], v[30:31] op_sel_hi:[1,0] neg_lo:[0,1] neg_hi:[0,1]
	v_pk_add_f32 v[10:11], v[56:57], v[30:31] op_sel_hi:[1,0] neg_lo:[0,1] neg_hi:[0,1]
	v_pk_mul_f32 v[56:57], v[16:17], v[16:17]
	v_pk_add_f32 v[42:43], v[2:3], v[30:31] op_sel_hi:[1,0] neg_lo:[0,1] neg_hi:[0,1]
	v_pk_add_f32 v[6:7], v[26:27], v[30:31] op_sel_hi:[1,0] neg_lo:[0,1] neg_hi:[0,1]
	v_pk_add_f32 v[26:27], v[36:37], v[30:31] op_sel_hi:[1,0] neg_lo:[0,1] neg_hi:[0,1]
	v_pk_add_f32 v[2:3], v[12:13], v[30:31] op_sel_hi:[1,0] neg_lo:[0,1] neg_hi:[0,1]
	v_pk_add_f32 v[36:37], v[68:69], v[30:31] op_sel_hi:[1,0] neg_lo:[0,1] neg_hi:[0,1]
	v_pk_add_f32 v[46:47], v[8:9], v[30:31] op_sel_hi:[1,0] neg_lo:[0,1] neg_hi:[0,1]
	v_pk_add_f32 v[12:13], v[4:5], v[30:31] op_sel_hi:[1,0] neg_lo:[0,1] neg_hi:[0,1]
	v_pk_add_f32 v[8:9], v[20:21], v[30:31] op_sel_hi:[1,0] neg_lo:[0,1] neg_hi:[0,1]
	v_pk_mul_f32 v[30:31], v[14:15], v[14:15]
	v_pk_fma_f32 v[56:57], v[40:41], v[40:41], v[56:57]
	v_pk_fma_f32 v[30:31], v[42:43], v[42:43], v[30:31]
	v_add_f32_e32 v56, v56, v57
	v_pk_mul_f32 v[62:63], v[12:13], v[12:13]
	v_add_f32_e32 v30, v30, v56
	v_pk_fma_f32 v[62:63], v[46:47], v[46:47], v[62:63]
	v_add_f32_e32 v30, v31, v30
	v_pk_mul_f32 v[60:61], v[10:11], v[10:11]
	v_add_f32_e32 v30, v62, v30
	v_pk_fma_f32 v[60:61], v[36:37], v[36:37], v[60:61]
	v_add_f32_e32 v30, v63, v30
	v_pk_mul_f32 v[64:65], v[8:9], v[8:9]
	v_add_f32_e32 v30, v60, v30
	v_pk_fma_f32 v[64:65], v[58:59], v[58:59], v[64:65]
	v_add_f32_e32 v30, v61, v30
	v_pk_mul_f32 v[4:5], v[6:7], v[6:7]
	v_add_f32_e32 v30, v64, v30
	v_pk_fma_f32 v[4:5], v[44:45], v[44:45], v[4:5]
	v_add_f32_e32 v30, v65, v30
	v_pk_mul_f32 v[18:19], v[0:1], v[0:1]
	v_add_f32_e32 v4, v4, v30
	v_pk_fma_f32 v[18:19], v[26:27], v[26:27], v[18:19]
	v_add_f32_e32 v4, v5, v4
	v_pk_mul_f32 v[20:21], v[2:3], v[2:3]
	v_add_f32_e32 v4, v19, v4
	v_pk_fma_f32 v[20:21], v[24:25], v[24:25], v[20:21]
	v_add_f32_e32 v4, v18, v4
	v_add_f32_e32 v4, v21, v4
	v_add_f32_e32 v4, v20, v4
	ds_bpermute_b32 v5, v169, v4
	v_rcp_f32_e32 v39, v39
	s_waitcnt lgkmcnt(0)
	v_add_f32_e32 v4, v4, v5
	v_fmamk_f32 v4, v4, 0x3c800000, v192
	v_mul_f32_e32 v5, 0x4b800000, v4
	v_cmp_gt_f32_e32 vcc, s27, v4
	s_nop 1
	v_cndmask_b32_e32 v4, v4, v5, vcc
	v_rsq_f32_e32 v4, v4
	s_nop 0
	v_mul_f32_e32 v5, 0x45800000, v4
	v_cndmask_b32_e32 v4, v4, v5, vcc
	v_pk_mul_f32 v[18:19], v[40:41], v[4:5] op_sel_hi:[1,0]
	v_pk_mul_f32 v[20:21], v[42:43], v[4:5] op_sel_hi:[1,0]
	v_pk_mul_f32 v[18:19], v[48:49], v[18:19]
	v_pk_mul_f32 v[20:21], v[50:51], v[20:21]
	v_pk_mul_f32 v[18:19], v[18:19], v[34:35]
	v_pk_mul_f32 v[20:21], v[20:21], v[28:29]
	v_pk_mul_f32 v[18:19], v[22:23], v[18:19]
	v_pk_mul_f32 v[20:21], v[38:39], v[20:21]
	v_cvt_pk_bf16_f32 v18, v18, v19
	v_cvt_pk_bf16_f32 v19, v20, v21
	global_store_dwordx2 v[164:165], v[18:19], off
	s_waitcnt vmcnt(14)
	v_lshlrev_b32_e32 v22, 16, v55
	v_and_b32_e32 v23, 0xffff0000, v55
	v_lshlrev_b32_e32 v28, 16, v54
	v_and_b32_e32 v29, 0xffff0000, v54
	v_mul_f32_e32 v5, 0xbfb8aa3b, v28
	v_mul_f32_e32 v30, 0xbfb8aa3b, v29
	v_mul_f32_e32 v31, 0xbfb8aa3b, v22
	v_mul_f32_e32 v34, 0xbfb8aa3b, v23
	v_exp_f32_e32 v5, v5
	v_exp_f32_e32 v30, v30
	v_exp_f32_e32 v31, v31
	v_exp_f32_e32 v34, v34
	v_add_f32_e32 v5, 1.0, v5
	v_add_f32_e32 v35, 1.0, v30
	v_add_f32_e32 v38, 1.0, v31
	v_add_f32_e32 v39, 1.0, v34
	v_rcp_f32_e32 v30, v5
	v_rcp_f32_e32 v31, v35
	v_rcp_f32_e32 v34, v38
	v_rcp_f32_e32 v35, v39
	v_pk_mul_f32 v[38:39], v[46:47], v[4:5] op_sel_hi:[1,0]
	v_pk_mul_f32 v[36:37], v[36:37], v[4:5] op_sel_hi:[1,0]
	s_and_b64 vcc, exec, s[84:85]
	s_mov_b64 s[84:85], 0
	s_waitcnt vmcnt(11)
	v_pk_mul_f32 v[18:19], v[224:225], v[38:39]
	v_pk_mul_f32 v[20:21], v[226:227], v[36:37]
	v_pk_mul_f32 v[18:19], v[18:19], v[28:29]
	v_pk_mul_f32 v[20:21], v[20:21], v[22:23]
	v_pk_mul_f32 v[18:19], v[30:31], v[18:19]
	v_pk_mul_f32 v[20:21], v[34:35], v[20:21]
	v_cvt_pk_bf16_f32 v18, v18, v19
	v_cvt_pk_bf16_f32 v19, v20, v21
	global_store_dwordx2 v[164:165], v[18:19], off offset:16
	v_lshlrev_b32_e32 v22, 16, v52
	v_and_b32_e32 v23, 0xffff0000, v52
	v_lshlrev_b32_e32 v28, 16, v53
	v_and_b32_e32 v29, 0xffff0000, v53
	v_mul_f32_e32 v5, 0xbfb8aa3b, v22
	v_mul_f32_e32 v30, 0xbfb8aa3b, v23
	v_mul_f32_e32 v31, 0xbfb8aa3b, v28
	v_mul_f32_e32 v34, 0xbfb8aa3b, v29
	v_exp_f32_e32 v5, v5
	v_exp_f32_e32 v30, v30
	v_exp_f32_e32 v31, v31
	v_exp_f32_e32 v34, v34
	v_add_f32_e32 v5, 1.0, v5
	v_add_f32_e32 v35, 1.0, v30
	v_add_f32_e32 v36, 1.0, v31
	v_add_f32_e32 v37, 1.0, v34
	v_rcp_f32_e32 v30, v5
	v_rcp_f32_e32 v31, v35
	v_rcp_f32_e32 v34, v36
	v_rcp_f32_e32 v35, v37
	v_pk_mul_f32 v[36:37], v[58:59], v[4:5] op_sel_hi:[1,0]
	v_pk_mul_f32 v[38:39], v[44:45], v[4:5] op_sel_hi:[1,0]
	s_waitcnt vmcnt(11)
	v_pk_mul_f32 v[18:19], v[228:229], v[36:37]
	v_pk_mul_f32 v[20:21], v[230:231], v[38:39]
	v_pk_mul_f32 v[18:19], v[18:19], v[22:23]
	v_pk_mul_f32 v[20:21], v[20:21], v[28:29]
	v_pk_mul_f32 v[18:19], v[30:31], v[18:19]
	v_pk_mul_f32 v[20:21], v[34:35], v[20:21]
	v_cvt_pk_bf16_f32 v18, v18, v19
	v_cvt_pk_bf16_f32 v19, v20, v21
	global_store_dwordx2 v[164:165], v[18:19], off offset:32
	v_lshlrev_b32_e32 v28, 16, v32
	v_and_b32_e32 v29, 0xffff0000, v32
	v_lshlrev_b32_e32 v30, 16, v33
	v_and_b32_e32 v31, 0xffff0000, v33
	v_mul_f32_e32 v5, 0xbfb8aa3b, v28
	v_mul_f32_e32 v32, 0xbfb8aa3b, v29
	v_mul_f32_e32 v33, 0xbfb8aa3b, v30
	v_mul_f32_e32 v34, 0xbfb8aa3b, v31
	v_exp_f32_e32 v5, v5
	v_exp_f32_e32 v32, v32
	v_exp_f32_e32 v33, v33
	v_exp_f32_e32 v34, v34
	v_add_f32_e32 v5, 1.0, v5
	v_add_f32_e32 v35, 1.0, v32
	v_add_f32_e32 v36, 1.0, v33
	v_add_f32_e32 v37, 1.0, v34
	v_rcp_f32_e32 v32, v5
	v_rcp_f32_e32 v33, v35
	v_rcp_f32_e32 v34, v36
	v_rcp_f32_e32 v35, v37
	v_pk_mul_f32 v[26:27], v[26:27], v[4:5] op_sel_hi:[1,0]
	v_pk_mul_f32 v[24:25], v[24:25], v[4:5] op_sel_hi:[1,0]
	s_waitcnt vmcnt(11)
	v_pk_mul_f32 v[18:19], v[232:233], v[26:27] op_sel:[0,1] op_sel_hi:[1,0]
	v_pk_mul_f32 v[20:21], v[234:235], v[24:25] op_sel:[0,1] op_sel_hi:[1,0]
	v_pk_mul_f32 v[18:19], v[18:19], v[28:29]
	v_pk_mul_f32 v[20:21], v[20:21], v[30:31]
	v_pk_mul_f32 v[18:19], v[32:33], v[18:19]
	v_pk_mul_f32 v[20:21], v[34:35], v[20:21]
	v_cvt_pk_bf16_f32 v18, v18, v19
	v_cvt_pk_bf16_f32 v19, v20, v21
	global_store_dwordx2 v[164:165], v[18:19], off offset:48
	s_waitcnt vmcnt(7)
	v_lshlrev_b32_e32 v30, 16, v207
	v_and_b32_e32 v31, 0xffff0000, v207
	v_lshlrev_b32_e32 v32, 16, v206
	v_and_b32_e32 v33, 0xffff0000, v206
	v_mul_f32_e32 v5, 0xbfb8aa3b, v32
	v_mul_f32_e32 v22, 0xbfb8aa3b, v33
	v_mul_f32_e32 v23, 0xbfb8aa3b, v30
	v_mul_f32_e32 v34, 0xbfb8aa3b, v31
	v_exp_f32_e32 v5, v5
	v_exp_f32_e32 v22, v22
	v_exp_f32_e32 v23, v23
	v_exp_f32_e32 v34, v34
	v_add_f32_e32 v5, 1.0, v5
	v_add_f32_e32 v35, 1.0, v22
	v_add_f32_e32 v36, 1.0, v23
	v_add_f32_e32 v37, 1.0, v34
	v_rcp_f32_e32 v22, v5
	v_rcp_f32_e32 v23, v35
	v_rcp_f32_e32 v34, v36
	v_rcp_f32_e32 v35, v37
	v_pk_mul_f32 v[16:17], v[16:17], v[4:5] op_sel_hi:[1,0]
	v_pk_mul_f32 v[14:15], v[14:15], v[4:5] op_sel_hi:[1,0]
	v_pk_mul_f32 v[16:17], v[236:237], v[16:17]
	v_pk_mul_f32 v[14:15], v[238:239], v[14:15]
	v_pk_mul_f32 v[16:17], v[16:17], v[32:33]
	v_pk_mul_f32 v[14:15], v[14:15], v[30:31]
	v_pk_mul_f32 v[16:17], v[22:23], v[16:17]
	v_pk_mul_f32 v[14:15], v[34:35], v[14:15]
	v_cvt_pk_bf16_f32 v16, v16, v17
	v_cvt_pk_bf16_f32 v17, v14, v15
	global_store_dwordx2 v[164:165], v[16:17], off offset:64
	s_waitcnt vmcnt(7)
	v_lshlrev_b32_e32 v18, 16, v209
	v_and_b32_e32 v19, 0xffff0000, v209
	v_lshlrev_b32_e32 v20, 16, v208
	v_and_b32_e32 v21, 0xffff0000, v208
	v_mul_f32_e32 v5, 0xbfb8aa3b, v20
	v_mul_f32_e32 v22, 0xbfb8aa3b, v21
	v_mul_f32_e32 v23, 0xbfb8aa3b, v18
	v_mul_f32_e32 v24, 0xbfb8aa3b, v19
	v_exp_f32_e32 v5, v5
	v_exp_f32_e32 v22, v22
	v_exp_f32_e32 v23, v23
	v_exp_f32_e32 v24, v24
	v_add_f32_e32 v5, 1.0, v5
	v_add_f32_e32 v25, 1.0, v22
	v_add_f32_e32 v30, 1.0, v23
	v_add_f32_e32 v31, 1.0, v24
	v_rcp_f32_e32 v22, v5
	v_rcp_f32_e32 v23, v25
	v_rcp_f32_e32 v24, v30
	v_rcp_f32_e32 v25, v31
	v_pk_mul_f32 v[12:13], v[12:13], v[4:5] op_sel_hi:[1,0]
	v_pk_mul_f32 v[10:11], v[10:11], v[4:5] op_sel_hi:[1,0]
	v_pk_mul_f32 v[12:13], v[240:241], v[12:13]
	v_pk_mul_f32 v[10:11], v[242:243], v[10:11]
	v_pk_mul_f32 v[12:13], v[12:13], v[20:21]
	v_pk_mul_f32 v[10:11], v[10:11], v[18:19]
	v_pk_mul_f32 v[12:13], v[22:23], v[12:13]
	v_pk_mul_f32 v[10:11], v[24:25], v[10:11]
	v_cvt_pk_bf16_f32 v12, v12, v13
	v_cvt_pk_bf16_f32 v13, v10, v11
	global_store_dwordx2 v[164:165], v[12:13], off offset:80
	s_waitcnt vmcnt(7)
	v_lshlrev_b32_e32 v14, 16, v210
	v_and_b32_e32 v15, 0xffff0000, v210
	v_lshlrev_b32_e32 v16, 16, v211
	v_and_b32_e32 v17, 0xffff0000, v211
	v_mul_f32_e32 v5, 0xbfb8aa3b, v14
	v_mul_f32_e32 v18, 0xbfb8aa3b, v15
	v_mul_f32_e32 v19, 0xbfb8aa3b, v16
	v_mul_f32_e32 v20, 0xbfb8aa3b, v17
	v_exp_f32_e32 v5, v5
	v_exp_f32_e32 v18, v18
	v_exp_f32_e32 v19, v19
	v_exp_f32_e32 v20, v20
	v_add_f32_e32 v5, 1.0, v5
	v_add_f32_e32 v21, 1.0, v18
	v_add_f32_e32 v22, 1.0, v19
	v_add_f32_e32 v23, 1.0, v20
	v_rcp_f32_e32 v18, v5
	v_rcp_f32_e32 v19, v21
	v_rcp_f32_e32 v20, v22
	v_rcp_f32_e32 v21, v23
	v_pk_mul_f32 v[8:9], v[8:9], v[4:5] op_sel_hi:[1,0]
	v_pk_mul_f32 v[6:7], v[6:7], v[4:5] op_sel_hi:[1,0]
	v_pk_mul_f32 v[8:9], v[244:245], v[8:9]
	v_pk_mul_f32 v[6:7], v[246:247], v[6:7]
	v_pk_mul_f32 v[8:9], v[8:9], v[14:15]
	v_pk_mul_f32 v[6:7], v[6:7], v[16:17]
	v_pk_mul_f32 v[8:9], v[18:19], v[8:9]
	v_pk_mul_f32 v[6:7], v[20:21], v[6:7]
	v_cvt_pk_bf16_f32 v8, v8, v9
	v_cvt_pk_bf16_f32 v9, v6, v7
	global_store_dwordx2 v[164:165], v[8:9], off offset:96
	s_waitcnt vmcnt(7)
	v_lshlrev_b32_e32 v10, 16, v212
	v_and_b32_e32 v11, 0xffff0000, v212
	v_lshlrev_b32_e32 v12, 16, v213
	v_and_b32_e32 v13, 0xffff0000, v213
	v_mul_f32_e32 v5, 0xbfb8aa3b, v10
	v_mul_f32_e32 v14, 0xbfb8aa3b, v11
	v_mul_f32_e32 v15, 0xbfb8aa3b, v12
	v_mul_f32_e32 v16, 0xbfb8aa3b, v13
	v_exp_f32_e32 v5, v5
	v_exp_f32_e32 v14, v14
	v_exp_f32_e32 v15, v15
	v_exp_f32_e32 v16, v16
	v_add_f32_e32 v5, 1.0, v5
	v_add_f32_e32 v17, 1.0, v14
	v_add_f32_e32 v18, 1.0, v15
	v_add_f32_e32 v19, 1.0, v16
	v_rcp_f32_e32 v14, v5
	v_rcp_f32_e32 v15, v17
	v_rcp_f32_e32 v16, v18
	v_rcp_f32_e32 v17, v19
	v_pk_mul_f32 v[0:1], v[0:1], v[4:5] op_sel_hi:[1,0]
	v_pk_mul_f32 v[2:3], v[2:3], v[4:5] op_sel_hi:[1,0]
	v_pk_mul_f32 v[0:1], v[248:249], v[0:1] op_sel:[0,1] op_sel_hi:[1,0]
	v_pk_mul_f32 v[2:3], v[250:251], v[2:3] op_sel:[0,1] op_sel_hi:[1,0]
	v_pk_mul_f32 v[0:1], v[0:1], v[10:11]
	v_pk_mul_f32 v[2:3], v[2:3], v[12:13]
	v_pk_mul_f32 v[0:1], v[14:15], v[0:1]
	v_pk_mul_f32 v[2:3], v[16:17], v[2:3]
	v_cvt_pk_bf16_f32 v0, v0, v1
	v_cvt_pk_bf16_f32 v1, v2, v3
	global_store_dwordx2 v[164:165], v[0:1], off offset:112
	s_barrier
	s_cbranch_vccnz .LBB0_548
	s_add_i32 s86, s86, s26
	s_cmpk_gt_i32 s86, 0xff
	s_cbranch_scc0 .LBB0_540
	s_branch .LBB0_551
